# post_item unit loop: three units of row loads in flight (v40-55, v212-227, v228-243) instead of one
# baseline (speedup 1.0000x reference)
; #define LAS __attribute__((address_space(3)))
; DI float sigm(float x) { return __builtin_amdgcn_rcpf(1.f + __expf(-x)); }
; DI u32x4 pack8(const float* f) { u32x4 w; w.x = pk2(f[0], f[1]); w.y = pk2(f[2], f[3]); w.z = pk2(f[4], f[5]); w.w = pk2(f[6], f[7]); return w; }
; DI void post_item(const Args& a, int l, int item, LAS unsigned char* lds) {
;     ...
;         const int token = tid >> 3, part = tid & 7; const size_t row = (size_t)b * SEQ + t0 + token; const bool hp = (t0 + token) > 0;
; #pragma unroll
;         for (int hf = 0; hf < 2; ++hf) {
;             float v[8]; const int cc = part * 16 + hf * 8;
;             lerp8(PROJ + row * PP + C_GL + cc, PROJ + (row - 1) * PP + C_GL + cc, hp, mu + (C_GL - C_R) + cc, v);
; #pragma unroll
;             for (int i = 0; i < 8; ++i) v[i] = sigm(v[i]);
;             *(LAS u32x4*)(A_g + token * 136 + cc) = pack8(v);
;         }
;     }
;     {
;         const int cgp = tid & 63, head = cgp >> 3, k0 = (cgp & 7) * 8, c = cgp * 8;
;         float rk[8], lw[8], lb[8];
;         {
;             const float* srcs[3] = {a.in[I_RK] + l * 512 + c, a.in[I_LNW] + l * 512 + c, a.in[I_LNB] + l * 512 + c};
;             float* dsts[3] = {rk, lw, lb};
; #pragma unroll
;             for (int q = 0; q < 3; ++q) { const f32x4 t0v = *(const f32x4*)srcs[q], t1v = *(const f32x4*)(srcs[q] + 4);
; #pragma unroll
;                 for (int i = 0; i < 4; ++i) { dsts[q][i] = t0v[i]; dsts[q][4 + i] = t1v[i]; } }
;         }
;         u32x4 raw[4];
;         auto load_unit = [&](int u) {
;             const int token = u * 8 + (tid >> 6); const size_t row = (size_t)b * SEQ + t0 + token;
;             raw[0] = *(const u32x4*)((const bf16_t*)(a.ws + WS_Y) + row * 512 + c);
;             const bf16_t* ip = PREP + ((size_t)(b * 8 + head) * SEQ + t0 + token) * 192 + k0;
;             raw[1] = *(const u32x4*)ip; raw[2] = *(const u32x4*)(ip + 64); raw[3] = *(const u32x4*)(ip + 128);
;         };
;         load_unit(0);
.LBB0_200:
	s_or_b64 exec, exec, s[20:21]
	v_lshlrev_b32_e32 v9, 2, v9
	global_load_dwordx4 v[10:13], v9, s[0:1] offset:16
	global_load_dwordx4 v[14:17], v9, s[0:1]
	s_waitcnt vmcnt(2)
	v_lshlrev_b32_e32 v9, 16, v0
	v_lshlrev_b32_e32 v18, 16, v4
	v_and_b32_e32 v4, 0xffff0000, v4
	v_and_b32_e32 v0, 0xffff0000, v0
	v_sub_f32_e32 v9, v9, v18
	v_sub_f32_e32 v0, v0, v4
	v_bfe_u32 v29, v64, 3, 3
	v_ashrrev_i32_e32 v62, 6, v64
	v_readlane_b32 s24, v247, 34
	v_ashrrev_i32_e32 v63, 31, v62
	v_lshl_or_b32 v42, s18, 3, v29
	v_readlane_b32 s25, v247, 35
	v_ashrrev_i32_e32 v43, 31, v42
	v_lshlrev_b64 v[30:31], 12, v[42:43]
	v_lshl_add_u64 v[32:33], v[62:63], 0, s[24:25]
	v_readlane_b32 s24, v245, 28
	v_readlane_b32 s26, v247, 36
	v_readlane_b32 s25, v245, 29
	v_and_b32_e32 v26, 63, v64
	v_lshl_add_u64 v[60:61], s[16:17], 0, v[62:63]
	v_lshl_add_u64 v[30:31], v[32:33], 0, v[30:31]
	v_mov_b64_e32 v[32:33], s[24:25]
	s_movk_i32 s26, 0x180
	v_lshlrev_b32_e32 v20, 5, v26
	v_lshlrev_b64 v[24:25], 10, v[60:61]
	v_mad_u64_u32 v[32:33], s[24:25], v30, s26, v[32:33]
	v_lshl_add_u64 v[24:25], s[10:11], 0, v[24:25]
	v_lshlrev_b32_e32 v40, 4, v26
	v_mov_b32_e32 v41, v129
	v_mad_i32_i24 v33, v31, s26, v33
	v_mov_b32_e32 v29, v129
	v_lshl_add_u64 v[24:25], v[24:25], 0, v[40:41]
	v_lshl_add_u64 v[28:29], v[32:33], 0, v[28:29]
	s_bfe_u32 s20, s22, 0x60006
	s_movk_i32 s21, 0xfc00
	s_mulk_i32 s20, 0x6000
	v_and_or_b32 v41, v44, s21, v40
	v_readlane_b32 s21, v246, 12
	v_mov_b32_e32 v128, s20
	s_lshl_b32 s20, s22, 10
	v_add_u32_e32 v66, s21, v41
	s_mov_b32 s21, 0x180000
	v_mad_i64_i32 v[42:43], s[24:25], v42, s21, v[128:129]
	v_mad_i64_i32 v[42:43], s[24:25], v62, s26, v[42:43]
	v_and_b32_e32 v41, 7, v64
	s_and_b32 s20, s20, 0x3f0000
	v_lshl_or_b32 v42, v41, 4, v42
	s_lshl_b64 s[18:19], s[18:19], 22
	v_lshl_add_u64 v[56:57], s[12:13], 0, v[42:43]
	s_or_b32 s18, s18, s20
	v_lshlrev_b64 v[42:43], 10, v[62:63]
	v_lshl_add_u64 v[42:43], s[18:19], 0, v[42:43]
	v_or_b32_e32 v42, v42, v40
	v_lshl_add_u64 v[58:59], s[14:15], 0, v[42:43]
	v_lshlrev_b32_e32 v65, 3, v64
	s_mov_b32 s18, 0
	v_readlane_b32 s27, v247, 37
	s_waitcnt vmcnt(0)
	v_fmac_f32_e32 v18, v14, v9
	v_fmac_f32_e32 v4, v15, v0
	v_lshlrev_b32_e32 v0, 16, v1
	v_lshlrev_b32_e32 v9, 16, v5
	v_sub_f32_e32 v0, v0, v9
	v_fmac_f32_e32 v9, v16, v0
	v_and_b32_e32 v0, 0xffff0000, v5
	v_and_b32_e32 v1, 0xffff0000, v1
	v_sub_f32_e32 v1, v1, v0
	v_fmac_f32_e32 v0, v17, v1
	v_lshlrev_b32_e32 v1, 16, v2
	v_lshlrev_b32_e32 v5, 16, v6
	v_mul_f32_e32 v0, 0xbfb8aa3b, v0
	v_sub_f32_e32 v1, v1, v5
	v_exp_f32_e32 v0, v0
	v_fmac_f32_e32 v5, v10, v1
	v_and_b32_e32 v1, 0xffff0000, v6
	v_and_b32_e32 v2, 0xffff0000, v2
	v_sub_f32_e32 v2, v2, v1
	v_fmac_f32_e32 v1, v11, v2
	v_lshlrev_b32_e32 v2, 16, v3
	v_lshlrev_b32_e32 v6, 16, v7
	v_sub_f32_e32 v2, v2, v6
	v_add_f32_e32 v0, 1.0, v0
	v_fmac_f32_e32 v6, v12, v2
	v_and_b32_e32 v2, 0xffff0000, v7
	v_mul_f32_e32 v7, 0xbfb8aa3b, v9
	v_rcp_f32_e32 v9, v0
	v_mul_f32_e32 v0, 0xbfb8aa3b, v5
	v_exp_f32_e32 v0, v0
	v_and_b32_e32 v3, 0xffff0000, v3
	v_sub_f32_e32 v3, v3, v2
	v_fmac_f32_e32 v2, v13, v3
	v_add_f32_e32 v0, 1.0, v0
	v_rcp_f32_e32 v5, v0
	v_mul_f32_e32 v0, 0xbfb8aa3b, v1
	v_exp_f32_e32 v0, v0
	v_mul_f32_e32 v3, 0xbfb8aa3b, v18
	v_mul_f32_e32 v4, 0xbfb8aa3b, v4
	v_exp_f32_e32 v3, v3
	v_add_f32_e32 v0, 1.0, v0
	v_rcp_f32_e32 v10, v0
	v_mul_f32_e32 v0, 0xbfb8aa3b, v6
	v_exp_f32_e32 v0, v0
	v_exp_f32_e32 v4, v4
	v_exp_f32_e32 v7, v7
	v_add_f32_e32 v3, 1.0, v3
	v_add_f32_e32 v0, 1.0, v0
	v_rcp_f32_e32 v6, v0
	v_mul_f32_e32 v0, 0xbfb8aa3b, v2
	v_exp_f32_e32 v0, v0
	v_add_f32_e32 v4, 1.0, v4
	v_add_f32_e32 v7, 1.0, v7
	v_rcp_f32_e32 v3, v3
	v_add_f32_e32 v0, 1.0, v0
	v_rcp_f32_e32 v4, v4
	v_rcp_f32_e32 v7, v7
	v_rcp_f32_e32 v11, v0
	v_cvt_pk_bf16_f32 v2, v5, v10
	v_cvt_pk_bf16_f32 v0, v3, v4
	v_cvt_pk_bf16_f32 v1, v7, v9
	v_cvt_pk_bf16_f32 v3, v6, v11
	ds_write_b128 v8, v[0:3] offset:16
	global_load_dwordx4 v[0:3], v20, s[4:5]
	global_load_dwordx4 v[4:7], v20, s[4:5] offset:16
	global_load_dwordx4 v[8:11], v20, s[6:7]
	global_load_dwordx4 v[12:15], v20, s[6:7] offset:16
	global_load_dwordx4 v[16:19], v20, s[8:9]
	s_nop 0
	global_load_dwordx4 v[20:23], v20, s[8:9] offset:16
	s_nop 0
	global_load_dwordx4 v[24:27], v[24:25], off
	s_nop 0
	global_load_dwordx4 v[36:39], v[28:29], off
	global_load_dwordx4 v[32:35], v[28:29], off offset:128
	s_nop 0
	global_load_dwordx4 v[28:31], v[28:29], off offset:256
	global_load_dwordx4 v[40:43], v[58:59], off
	global_load_dwordx4 v[44:47], v[56:57], off offset:-128
	global_load_dwordx4 v[48:51], v[56:57], off
	global_load_dwordx4 v[52:55], v[56:57], off offset:128
	s_mov_b64 s[20:21], 0x2000
	v_lshl_add_u64 v[58:59], v[58:59], 0, s[20:21]
	s_mov_b64 s[20:21], 0xc00
	v_lshl_add_u64 v[56:57], v[56:57], 0, s[20:21]
	global_load_dwordx4 v[212:215], v[58:59], off
	global_load_dwordx4 v[216:219], v[56:57], off offset:-128
	global_load_dwordx4 v[220:223], v[56:57], off
	global_load_dwordx4 v[224:227], v[56:57], off offset:128
	s_mov_b64 s[20:21], 0x2000
	v_lshl_add_u64 v[58:59], v[58:59], 0, s[20:21]
	s_mov_b64 s[20:21], 0xc00
	v_lshl_add_u64 v[56:57], v[56:57], 0, s[20:21]
	global_load_dwordx4 v[228:231], v[58:59], off
	global_load_dwordx4 v[232:235], v[56:57], off offset:-128
	global_load_dwordx4 v[236:239], v[56:57], off
	global_load_dwordx4 v[240:243], v[56:57], off offset:128
	s_waitcnt vmcnt(12)
	s_branch .LBB0_201
; #define LAS __attribute__((address_space(3)))
; DI void unpack8(const u32x4 w, float* f) { f[0] = bflo(w.x); f[1] = bfhi(w.x); f[2] = bflo(w.y); f[3] = bfhi(w.y); f[4] = bflo(w.z); f[5] = bfhi(w.z); f[6] = bflo(w.w); f[7] = bfhi(w.w); }
; DI u32x4 pack8(const float* f) { u32x4 w; w.x = pk2(f[0], f[1]); w.y = pk2(f[2], f[3]); w.z = pk2(f[4], f[5]); w.w = pk2(f[6], f[7]); return w; }
; DI float red8(float x) { x = red4(x); x = dpp_add<0x141>(x); return x; }
; DI void post_item(const Args& a, int l, int item, LAS unsigned char* lds) {
;     ...
;         for (int u = 0; u < 8; ++u) {
;             const int token = u * 8 + (tid >> 6);
;             float y[8], r[8], k[8], v[8];
;             unpack8(raw[0], y); unpack8(raw[1], r); unpack8(raw[2], k); unpack8(raw[3], v);
;             if (u + 1 < 8) load_unit(u + 1);
;             float sm = 0.f;
; #pragma unroll
;             for (int i = 0; i < 8; ++i) sm += y[i];
;             const float mean = red8(sm) * (1.f / 64.f);
;             float sv = 0.f;
; #pragma unroll
;             for (int i = 0; i < 8; ++i) { y[i] -= mean; sv += y[i] * y[i]; }
;             const float rstd = rsqrtf(red8(sv) * (1.f / 64.f) + 64e-5f);
;             float dot = 0.f;
; #pragma unroll
;             for (int i = 0; i < 8; ++i) dot += r[i] * k[i] * rk[i];
;             dot = red8(dot);
;             float z[8];
; #pragma unroll
;             for (int i = 0; i < 8; ++i) z[i] = y[i] * rstd * lw[i] + lb[i] + dot * v[i];
;             *(LAS u32x4*)(z_s + token * 512 + c) = pack8(z);
.LBB0_201:
	v_lshlrev_b32_e32 v68, 16, v24
	v_and_b32_e32 v69, 0xffff0000, v24
	v_add_f32_e32 v63, 0, v68
	v_lshlrev_b32_e32 v24, 16, v25
	v_add_f32_e32 v63, v63, v69
	v_and_b32_e32 v25, 0xffff0000, v25
	v_add_f32_e32 v63, v63, v24
	v_lshlrev_b32_e32 v70, 16, v26
	v_add_f32_e32 v63, v63, v25
	v_and_b32_e32 v71, 0xffff0000, v26
	v_add_f32_e32 v63, v63, v70
	v_lshlrev_b32_e32 v26, 16, v27
	v_add_f32_e32 v63, v63, v71
	v_and_b32_e32 v27, 0xffff0000, v27
	v_add_f32_e32 v63, v63, v26
	v_and_b32_e32 v73, 0xffff0000, v36
	v_lshlrev_b32_e32 v72, 16, v36
	v_and_b32_e32 v75, 0xffff0000, v37
	v_lshlrev_b32_e32 v74, 16, v37
	v_and_b32_e32 v37, 0xffff0000, v38
	v_lshlrev_b32_e32 v36, 16, v38
	v_and_b32_e32 v77, 0xffff0000, v39
	v_lshlrev_b32_e32 v76, 16, v39
	v_and_b32_e32 v39, 0xffff0000, v32
	v_lshlrev_b32_e32 v38, 16, v32
	v_add_f32_e32 v63, v63, v27
	v_pk_mul_f32 v[38:39], v[38:39], v[72:73]
	v_and_b32_e32 v79, 0xffff0000, v33
	v_add_f32_dpp v63, v63, v63 quad_perm:[1,0,3,2] row_mask:0xf bank_mask:0xf bound_ctrl:1
	v_pk_mul_f32 v[38:39], v[0:1], v[38:39]
	v_lshlrev_b32_e32 v78, 16, v33
	v_add_f32_dpp v63, v63, v63 quad_perm:[2,3,0,1] row_mask:0xf bank_mask:0xf bound_ctrl:1
	v_add_f32_e32 v38, 0, v38
	v_and_b32_e32 v33, 0xffff0000, v34
	v_add_f32_dpp v63, v63, v63 row_half_mirror row_mask:0xf bank_mask:0xf bound_ctrl:1
	v_mul_f32_e32 v84, 0x3c800000, v63
	v_add_f32_e32 v63, v39, v38
	v_pk_mul_f32 v[38:39], v[78:79], v[74:75]
	v_lshlrev_b32_e32 v32, 16, v34
	v_pk_mul_f32 v[38:39], v[2:3], v[38:39]
	v_pk_mul_f32 v[32:33], v[32:33], v[36:37]
	v_add_f32_e32 v38, v38, v63
	v_add_f32_e32 v38, v39, v38
	v_pk_mul_f32 v[32:33], v[4:5], v[32:33]
	v_and_b32_e32 v81, 0xffff0000, v35
	v_lshlrev_b32_e32 v80, 16, v35
	v_add_f32_e32 v32, v32, v38
	v_add_f32_e32 v36, v33, v32
	v_pk_mul_f32 v[32:33], v[80:81], v[76:77]
	v_pk_add_f32 v[68:69], v[68:69], v[84:85] op_sel_hi:[1,0] neg_lo:[0,1] neg_hi:[0,1]
	v_pk_mul_f32 v[32:33], v[6:7], v[32:33]
	v_pk_add_f32 v[24:25], v[24:25], v[84:85] op_sel_hi:[1,0] neg_lo:[0,1] neg_hi:[0,1]
	v_pk_mul_f32 v[72:73], v[68:69], v[68:69]
	v_add_f32_e32 v32, v32, v36
	v_pk_add_f32 v[36:37], v[70:71], v[84:85] op_sel_hi:[1,0] neg_lo:[0,1] neg_hi:[0,1]
	v_pk_mul_f32 v[70:71], v[24:25], v[24:25]
	v_add_f32_e32 v67, v72, v73
	v_add_f32_e32 v67, v70, v67
	v_pk_mul_f32 v[38:39], v[36:37], v[36:37]
	v_add_f32_e32 v67, v71, v67
	v_pk_add_f32 v[26:27], v[26:27], v[84:85] op_sel_hi:[1,0] neg_lo:[0,1] neg_hi:[0,1]
	v_add_f32_e32 v38, v38, v67
	v_add_f32_e32 v63, v33, v32
	v_pk_mul_f32 v[32:33], v[26:27], v[26:27]
	v_add_f32_e32 v38, v39, v38
	v_add_f32_e32 v32, v32, v38
	v_add_f32_e32 v32, v33, v32
	s_mov_b32 s19, 0x800000
	v_lshlrev_b32_e32 v34, 16, v28
	v_add_f32_dpp v32, v32, v32 quad_perm:[1,0,3,2] row_mask:0xf bank_mask:0xf bound_ctrl:1
	v_and_b32_e32 v35, 0xffff0000, v28
	v_lshlrev_b32_e32 v28, 16, v29
	v_add_f32_dpp v32, v32, v32 quad_perm:[2,3,0,1] row_mask:0xf bank_mask:0xf bound_ctrl:1
	v_and_b32_e32 v29, 0xffff0000, v29
	v_lshlrev_b32_e32 v82, 16, v30
	v_add_f32_dpp v32, v32, v32 row_half_mirror row_mask:0xf bank_mask:0xf bound_ctrl:1
	v_fmamk_f32 v32, v32, 0x3c800000, v189
	v_mul_f32_e32 v33, 0x4b800000, v32
	v_cmp_gt_f32_e32 vcc, s19, v32
	v_and_b32_e32 v83, 0xffff0000, v30
	v_lshlrev_b32_e32 v30, 16, v31
	v_cndmask_b32_e32 v32, v32, v33, vcc
	v_rsq_f32_e32 v33, v32
	v_and_b32_e32 v31, 0xffff0000, v31
	v_add_f32_dpp v32, v63, v63 quad_perm:[1,0,3,2] row_mask:0xf bank_mask:0xf bound_ctrl:1
	s_mov_b64 s[20:21], 0xc00
	v_mul_f32_e32 v38, 0x45800000, v33
	v_cndmask_b32_e32 v38, v33, v38, vcc
	v_add_f32_dpp v32, v32, v32 quad_perm:[2,3,0,1] row_mask:0xf bank_mask:0xf bound_ctrl:1
	v_pk_mul_f32 v[24:25], v[24:25], v[38:39] op_sel_hi:[1,0]
	v_pk_mul_f32 v[68:69], v[68:69], v[38:39] op_sel_hi:[1,0]
	v_add_f32_dpp v32, v32, v32 row_half_mirror row_mask:0xf bank_mask:0xf bound_ctrl:1
	v_pk_fma_f32 v[24:25], v[10:11], v[24:25], v[18:19]
	v_pk_fma_f32 v[68:69], v[8:9], v[68:69], v[16:17]
	v_pk_fma_f32 v[28:29], v[32:33], v[28:29], v[24:25] op_sel_hi:[0,1,1]
	v_pk_mul_f32 v[24:25], v[36:37], v[38:39] op_sel_hi:[1,0]
	v_pk_fma_f32 v[34:35], v[32:33], v[34:35], v[68:69] op_sel_hi:[0,1,1]
	v_pk_fma_f32 v[24:25], v[12:13], v[24:25], v[20:21]
	v_lshl_add_u64 v[56:57], v[56:57], 0, s[20:21]
	v_pk_fma_f32 v[36:37], v[32:33], v[82:83], v[24:25] op_sel_hi:[0,1,1]
	v_pk_mul_f32 v[24:25], v[26:27], v[38:39] op_sel_hi:[1,0]
	v_cvt_pk_bf16_f32 v26, v36, v37
	v_pk_fma_f32 v[24:25], v[14:15], v[24:25], v[22:23]
	s_mov_b64 s[20:21], 0x2000
	v_pk_fma_f32 v[30:31], v[32:33], v[30:31], v[24:25] op_sel_hi:[0,1,1]
	v_cvt_pk_bf16_f32 v24, v34, v35
	v_cvt_pk_bf16_f32 v25, v28, v29
	v_cvt_pk_bf16_f32 v27, v30, v31
	v_add_u32_e32 v28, s18, v66
	ds_write_b128 v28, v[24:27]
	s_addk_i32 s18, 0x2000
	v_lshl_add_u64 v[58:59], v[58:59], 0, s[20:21]
	s_cmp_eq_u32 s18, 0x10000
	s_cbranch_scc1 .LBB0_195
	s_cmp_eq_u32 s18, 0xe000
	s_cbranch_scc1 .Lpo_n7
	s_cmp_eq_u32 s18, 0xc000
	s_cbranch_scc1 .Lpo_n6
	s_waitcnt vmcnt(8)
	s_cmp_eq_u32 s18, 0x2000
	s_cbranch_scc1 .Lpo_s0
	s_cmp_eq_u32 s18, 0x8000
	s_cbranch_scc1 .Lpo_s0
	s_cmp_eq_u32 s18, 0x6000
	s_cbranch_scc1 .Lpo_s2
	v_mov_b64_e32 v[24:25], v[212:213]
	v_mov_b64_e32 v[26:27], v[214:215]
	v_mov_b64_e32 v[36:37], v[216:217]
	v_mov_b64_e32 v[38:39], v[218:219]
	v_mov_b64_e32 v[32:33], v[220:221]
	v_mov_b64_e32 v[34:35], v[222:223]
	v_mov_b64_e32 v[28:29], v[224:225]
	v_mov_b64_e32 v[30:31], v[226:227]
	s_branch .LBB0_202

; DI void unpack8(const u32x4 w, float* f) { f[0] = bflo(w.x); f[1] = bfhi(w.x); f[2] = bflo(w.y); f[3] = bfhi(w.y); f[4] = bflo(w.z); f[5] = bfhi(w.z); f[6] = bflo(w.w); f[7] = bfhi(w.w); }
; DI void post_item(const Args& a, int l, int item, LAS unsigned char* lds) {
;     ...
;         auto load_unit = [&](int u) {
;             const int token = u * 8 + (tid >> 6); const size_t row = (size_t)b * SEQ + t0 + token;
;             raw[0] = *(const u32x4*)((const bf16_t*)(a.ws + WS_Y) + row * 512 + c);
;             const bf16_t* ip = PREP + ((size_t)(b * 8 + head) * SEQ + t0 + token) * 192 + k0;
;             raw[1] = *(const u32x4*)ip; raw[2] = *(const u32x4*)(ip + 64); raw[3] = *(const u32x4*)(ip + 128);
;         };
;         load_unit(0);
; #pragma unroll 1
;         for (int u = 0; u < 8; ++u) {
;             const int token = u * 8 + (tid >> 6);
;             float y[8], r[8], k[8], v[8];
;             unpack8(raw[0], y); unpack8(raw[1], r); unpack8(raw[2], k); unpack8(raw[3], v);
;             if (u + 1 < 8) load_unit(u + 1);
.Lpo_s0:
	v_mov_b64_e32 v[24:25], v[40:41]
	v_mov_b64_e32 v[26:27], v[42:43]
	v_mov_b64_e32 v[36:37], v[44:45]
	v_mov_b64_e32 v[38:39], v[46:47]
	v_mov_b64_e32 v[32:33], v[48:49]
	v_mov_b64_e32 v[34:35], v[50:51]
	v_mov_b64_e32 v[28:29], v[52:53]
	v_mov_b64_e32 v[30:31], v[54:55]
	s_branch .LBB0_202
.Lpo_n6:
	s_waitcnt vmcnt(4)
.Lpo_s2:
	v_mov_b64_e32 v[24:25], v[228:229]
	v_mov_b64_e32 v[26:27], v[230:231]
	v_mov_b64_e32 v[36:37], v[232:233]
	v_mov_b64_e32 v[38:39], v[234:235]
	v_mov_b64_e32 v[32:33], v[236:237]
	v_mov_b64_e32 v[34:35], v[238:239]
	v_mov_b64_e32 v[28:29], v[240:241]
	v_mov_b64_e32 v[30:31], v[242:243]
	s_branch .LBB0_202
.LBB0_202:
	s_cmp_ge_u32 s18, 0xa000
	s_cbranch_scc1 .LBB0_201
	s_cmp_eq_u32 s18, 0x4000
	s_cbranch_scc1 .Lpo_l1
	s_cmp_eq_u32 s18, 0x6000
	s_cbranch_scc1 .Lpo_l2
	global_load_dwordx4 v[40:43], v[58:59], off
	global_load_dwordx4 v[44:47], v[56:57], off offset:-128
	global_load_dwordx4 v[48:51], v[56:57], off
	global_load_dwordx4 v[52:55], v[56:57], off offset:128
	s_branch .LBB0_201
.Lpo_l1:
	global_load_dwordx4 v[212:215], v[58:59], off
	global_load_dwordx4 v[216:219], v[56:57], off offset:-128
	global_load_dwordx4 v[220:223], v[56:57], off
	global_load_dwordx4 v[224:227], v[56:57], off offset:128
	s_branch .LBB0_201
.Lpo_l2:
	global_load_dwordx4 v[228:231], v[58:59], off
	global_load_dwordx4 v[232:235], v[56:57], off offset:-128
	global_load_dwordx4 v[236:239], v[56:57], off
	global_load_dwordx4 v[240:243], v[56:57], off offset:128
	s_branch .LBB0_201
